# P7/P9 GEMM: the trailing re-read loads issued in the last K iteration (no next unit) now re-read the unit's last two K-tiles, which are cache-hot, instead of its first two
# speedup vs baseline: 1.0046x; 1.0046x over previous
; template <class Epi, class Sched, bool ALIGN_EPI = false, bool SP2 = false>
; __device__ __forceinline__ void gemm_phase(PG8_LAS unsigned char* lds, const Gemm g, const Sched& S, const Epi& E) {
;     ...
;         const bool has_next = S.next(ui + 1, nxt);
;         const char* nA = has_next ? (const char*)g.A + (size_t)nxt.pm * tstep : cA; const char* nB = has_next ? (const char*)g.Bt + (size_t)nxt.pn * tstep : cB;
;         for (int t = 0; t < nt; t += 2) {
;             const bool last = (t == nt - 2);
;             const char* a1 = cA + (size_t)(t + 1) * kstep;
;             const char* a2 = last ? nA : cA + (size_t)(t + 2) * kstep; const char* b2 = last ? nB : cB + (size_t)(t + 2) * kstep;
;             const char* a3 = a2 + kstep; const char* b3 = b2 + kstep;
.LBB0_1025:
	s_add_u32 s0, s46, 0x100
	s_addc_u32 s1, s47, 0
	s_ashr_i32 s39, s38, 31
	s_lshl_b64 s[26:27], s[38:39], 19
	s_add_u32 s44, s76, s26
	s_addc_u32 s45, s77, s27
	s_and_b64 s[26:27], s[6:7], exec
	s_cselect_b32 s26, s45, s9
	s_cselect_b32 s27, s44, s8
	s_ashr_i32 s37, s36, 31
	s_lshl_b64 s[40:41], s[36:37], 19
	s_add_u32 s40, s10, s40
	s_addc_u32 s41, s11, s41
	s_and_b64 s[48:49], s[6:7], exec
	s_cselect_b32 s37, s41, s47
	s_cselect_b32 s39, s40, s46
	s_add_u32 s27, s27, 0x700
	s_addc_u32 s26, s26, 0
	s_add_u32 s39, s39, 0x700
	s_addc_u32 s37, s37, 0
	v_lshl_add_u64 v[142:143], s[8:9], 0, v[134:135]
	v_lshl_add_u64 v[144:145], s[8:9], 0, v[136:137]
	s_mov_b32 s43, -2
	s_mov_b64 s[46:47], 0

; template <class Epi, class Sched, bool ALIGN_EPI = false, bool SP2 = false>
; __device__ __forceinline__ void gemm_phase(PG8_LAS unsigned char* lds, const Gemm g, const Sched& S, const Epi& E) {
;     ...
;         const bool has_next = S.next(ui + 1, nxt);
;         const char* nA = has_next ? (const char*)g.A + (size_t)nxt.pm * tstep : cA; const char* nB = has_next ? (const char*)g.Bt + (size_t)nxt.pn * tstep : cB;
;         for (int t = 0; t < nt; t += 2) {
;             const bool last = (t == nt - 2);
;             const char* a1 = cA + (size_t)(t + 1) * kstep;
;             const char* a2 = last ? nA : cA + (size_t)(t + 2) * kstep; const char* b2 = last ? nB : cB + (size_t)(t + 2) * kstep;
;             const char* a3 = a2 + kstep; const char* b3 = b2 + kstep;
.LBB0_1252:
	v_cndmask_b32_e64 v142, 0, 1, s[4:5]
	v_cmp_ne_u32_e64 s[6:7], 1, v142
	s_andn2_b64 vcc, exec, s[4:5]
	s_mov_b64 s[22:23], s[14:15]
	s_add_u32 s22, s22, 0x1500
	s_addc_u32 s23, s23, 0
	s_cbranch_vccnz .LBB0_1254
	s_mul_i32 s5, s47, 0x160000
	s_mul_hi_i32 s4, s47, 0x160000
	s_add_u32 s22, s8, s5
	s_addc_u32 s23, s9, s4
.LBB0_1254:
	s_and_b64 vcc, exec, s[6:7]
	s_mov_b64 s[4:5], s[24:25]
	s_add_u32 s4, s4, 0x1500
	s_addc_u32 s5, s5, 0
	s_cbranch_vccnz .LBB0_1256
	s_mul_i32 s4, s46, 0x160000
	s_mul_hi_i32 s5, s46, 0x160000
	s_add_u32 s4, s10, s4
	s_addc_u32 s5, s11, s5
